# non-temporal hint also on the f32 row loads of the first norm and on the split-K partial loads
# speedup vs baseline: 1.0100x; 1.0047x over previous
; __device__ __forceinline__ unsigned cvt_pk_bf16(float lo, float hi) { unsigned r; asm volatile("v_cvt_pk_bf16_f32 %0, %1, %2" : "=v"(r) : "v"(lo), "v"(hi)); return r; }
; __device__ __forceinline__ float bf_lo(unsigned u) { return __uint_as_float(u << 16); }
; __device__ __forceinline__ float bf_hi(unsigned u) { return __uint_as_float(u & 0xffff0000u); }
; __global__ void __launch_bounds__(512, 2) fwd_kernel(const Args a) {
;     ...
;                     const bool lat = m < ML; const float* xr = lat ? xl + (size_t)m * D : xcs + (size_t)(m - ML) * D; const int vec = lat ? (m >> 13) : 2;
;                     const float* shp = ada + vec * 12288 + so; const float* scp = shp + 2048;
;                     f32x4 v[8]; float ss = 0.f;
;                     if (lat && lbf) { const u32x2* xq = (const u32x2*)(XBb + (size_t)m * D);
; #pragma unroll
;                         for (int j = 0; j < 8; ++j) { const u32x2 q = xq[64 * j + lane]; v[j] = (f32x4){bf_lo(q.x), bf_hi(q.x), bf_lo(q.y), bf_hi(q.y)}; }
;                     } else {
; #pragma unroll
;                         for (int j = 0; j < 8; ++j) v[j] = ((const f32x4*)xr)[64 * j + lane];
;                         if (lat) { u32x2* xw = (u32x2*)(XBb + (size_t)m * D);
; #pragma unroll
;                             for (int j = 0; j < 8; ++j) { u32x2 w; w.x = cvt_pk_bf16(v[j].x, v[j].y); w.y = cvt_pk_bf16(v[j].z, v[j].w); xw[64 * j + lane] = w; } }
.LBB0_446:
	s_andn2_b64 vcc, exec, s[34:35]
	v_lshlrev_b32_e32 v176, 4, v188
	s_cbranch_vccnz .LBB0_449
	v_readlane_b32 s64, v252, 18
	s_and_b64 s[34:35], s[0:1], exec
	v_readlane_b32 s65, v252, 19
	s_cselect_b32 s4, s21, s65
	s_cselect_b32 s14, s37, s64
	s_add_i32 s15, s40, 0xffffc000
	s_ashr_i32 s41, s40, 31
	s_and_b64 s[34:35], s[0:1], exec
	s_cselect_b32 s35, 0, s41
	s_cselect_b32 s34, s15, s40
	s_lshl_b64 s[34:35], s[34:35], 13
	s_add_u32 s34, s14, s34
	s_addc_u32 s35, s4, s35
	global_load_dwordx4 v[0:3], v176, s[34:35] nt
	global_load_dwordx4 v[4:7], v176, s[34:35] offset:1024 nt
	global_load_dwordx4 v[8:11], v176, s[34:35] offset:2048 nt
	global_load_dwordx4 v[12:15], v176, s[34:35] offset:3072 nt
	global_load_dwordx4 v[16:19], v107, s[34:35] nt
	global_load_dwordx4 v[20:23], v108, s[34:35] nt
	global_load_dwordx4 v[24:27], v109, s[34:35] nt
	global_load_dwordx4 v[28:31], v110, s[34:35] nt
	s_and_b64 vcc, exec, s[42:43]
	v_readlane_b32 s66, v252, 20
	v_readlane_b32 s67, v252, 21
	v_readlane_b32 s68, v252, 22
	v_readlane_b32 s69, v252, 23
	v_readlane_b32 s70, v252, 24
	v_readlane_b32 s71, v252, 25
	v_readlane_b32 s72, v252, 26
	v_readlane_b32 s73, v252, 27
	v_readlane_b32 s74, v252, 28
	v_readlane_b32 s75, v252, 29
	v_readlane_b32 s76, v252, 30
	v_readlane_b32 s77, v252, 31
	v_readlane_b32 s78, v252, 32
	v_readlane_b32 s79, v252, 33
	s_cbranch_vccz .LBB0_449
	s_lshl_b64 s[34:35], s[40:41], 12
	s_waitcnt vmcnt(0)
	v_cvt_pk_bf16_f32 v64, v0, v1
	v_cvt_pk_bf16_f32 v65, v2, v3
	v_lshl_add_u64 v[66:67], v[46:47], 0, s[34:35]
	global_store_dwordx2 v[66:67], v[64:65], off
	v_cvt_pk_bf16_f32 v64, v4, v5
	v_cvt_pk_bf16_f32 v65, v6, v7
	global_store_dwordx2 v[66:67], v[64:65], off offset:512
	v_cvt_pk_bf16_f32 v64, v8, v9
	v_cvt_pk_bf16_f32 v65, v10, v11
	global_store_dwordx2 v[66:67], v[64:65], off offset:1024
	v_cvt_pk_bf16_f32 v64, v12, v13
	v_cvt_pk_bf16_f32 v65, v14, v15
	global_store_dwordx2 v[66:67], v[64:65], off offset:1536
	v_cvt_pk_bf16_f32 v64, v16, v17
	v_cvt_pk_bf16_f32 v65, v18, v19
	global_store_dwordx2 v[66:67], v[64:65], off offset:2048
	v_cvt_pk_bf16_f32 v64, v20, v21
	v_cvt_pk_bf16_f32 v65, v22, v23
	global_store_dwordx2 v[66:67], v[64:65], off offset:2560
	v_cvt_pk_bf16_f32 v64, v24, v25
	v_cvt_pk_bf16_f32 v65, v26, v27
	global_store_dwordx2 v[66:67], v[64:65], off offset:3072
	v_cvt_pk_bf16_f32 v64, v28, v29
	v_cvt_pk_bf16_f32 v65, v30, v31
	global_store_dwordx2 v[66:67], v[64:65], off offset:3584

; __global__ void __launch_bounds__(512, 2) fwd_kernel(const Args a) {
;     ...
;                     if (!lat && nks > 0) {
;                         f32x4 ps[8];
; #pragma unroll
;                         for (int j = 0; j < 8; ++j) ps[j] = (f32x4){0.f, 0.f, 0.f, 0.f};
; #pragma unroll 2
;                         for (int kc = 0; kc < nks; ++kc) { const f32x4* pp = (const f32x4*)(PARTb + (size_t)kc * MC * D + (size_t)(m - ML) * D);
; #pragma unroll
;                             for (int j = 0; j < 8; ++j) ps[j] += pp[64 * j + lane]; }
.LBB0_452:
	s_mov_b32 s14, 0xffbff000
	v_add_co_u32_e32 v190, vcc, s14, v96
	s_mov_b32 s14, 0xffc00000
	s_nop 0
	v_addc_co_u32_e32 v191, vcc, -1, v97, vcc
	v_add_co_u32_e32 v192, vcc, s14, v96
	s_nop 1
	v_addc_co_u32_e32 v193, vcc, -1, v97, vcc
	v_add_co_u32_e32 v194, vcc, s95, v96
	s_nop 1
	v_addc_co_u32_e32 v195, vcc, -1, v97, vcc
	global_load_dwordx4 v[112:115], v[190:191], off offset:-3072 nt
	global_load_dwordx4 v[116:119], v[190:191], off offset:-2048 nt
	global_load_dwordx4 v[120:123], v[190:191], off offset:-1024 nt
	global_load_dwordx4 v[124:127], v[192:193], off offset:-4096 nt
	global_load_dwordx4 v[128:131], v[192:193], off offset:-3072 nt
	global_load_dwordx4 v[132:135], v[192:193], off offset:-2048 nt
	global_load_dwordx4 v[136:139], v[192:193], off offset:-1024 nt
	global_load_dwordx4 v[140:143], v[192:193], off nt
	global_load_dwordx4 v[144:147], v[194:195], off offset:-3072 nt
	global_load_dwordx4 v[148:151], v[194:195], off offset:-2048 nt
	global_load_dwordx4 v[152:155], v[194:195], off offset:-1024 nt
	global_load_dwordx4 v[156:159], v[96:97], off offset:-4096 nt
	global_load_dwordx4 v[160:163], v[96:97], off offset:-3072 nt
	global_load_dwordx4 v[164:167], v[96:97], off offset:-2048 nt
	global_load_dwordx4 v[168:171], v[96:97], off offset:-1024 nt
	global_load_dwordx4 v[172:175], v[96:97], off nt
	s_add_i32 s4, s4, 2
	s_mov_b64 s[34:35], 0x800000
	v_lshl_add_u64 v[96:97], v[96:97], 0, s[34:35]
	s_waitcnt vmcnt(8)
	v_pk_add_f32 v[92:93], v[92:93], v[112:113]
	v_pk_add_f32 v[94:95], v[94:95], v[114:115]
	v_pk_add_f32 v[88:89], v[88:89], v[116:117]
	v_pk_add_f32 v[90:91], v[90:91], v[118:119]
	v_pk_add_f32 v[84:85], v[84:85], v[120:121]
	v_pk_add_f32 v[86:87], v[86:87], v[122:123]
	v_pk_add_f32 v[70:71], v[70:71], v[124:125]
	v_pk_add_f32 v[72:73], v[72:73], v[126:127]
	v_pk_add_f32 v[80:81], v[80:81], v[128:129]
	v_pk_add_f32 v[82:83], v[82:83], v[130:131]
	v_pk_add_f32 v[76:77], v[76:77], v[132:133]
	v_pk_add_f32 v[78:79], v[78:79], v[134:135]
	v_pk_add_f32 v[74:75], v[74:75], v[136:137]
	v_pk_add_f32 v[68:69], v[68:69], v[138:139]
	v_pk_add_f32 v[64:65], v[64:65], v[140:141]
	v_pk_add_f32 v[66:67], v[66:67], v[142:143]
	s_waitcnt vmcnt(0)
	v_pk_add_f32 v[92:93], v[92:93], v[144:145]
	v_pk_add_f32 v[94:95], v[94:95], v[146:147]
	v_pk_add_f32 v[88:89], v[88:89], v[148:149]
	v_pk_add_f32 v[90:91], v[90:91], v[150:151]
	v_pk_add_f32 v[84:85], v[84:85], v[152:153]
	v_pk_add_f32 v[86:87], v[86:87], v[154:155]
	v_pk_add_f32 v[70:71], v[70:71], v[156:157]
	v_pk_add_f32 v[72:73], v[72:73], v[158:159]
	v_pk_add_f32 v[80:81], v[80:81], v[160:161]
	v_pk_add_f32 v[82:83], v[82:83], v[162:163]
	v_pk_add_f32 v[76:77], v[76:77], v[164:165]
	v_pk_add_f32 v[78:79], v[78:79], v[166:167]
	v_pk_add_f32 v[74:75], v[74:75], v[168:169]
	v_pk_add_f32 v[68:69], v[68:69], v[170:171]
	v_pk_add_f32 v[64:65], v[64:65], v[172:173]
	v_pk_add_f32 v[66:67], v[66:67], v[174:175]
	s_cmp_eq_u32 s44, s4
	s_cbranch_scc0 .LBB0_452
	s_andn2_b64 vcc, exec, s[30:31]
	s_cbranch_vccnz .LBB0_455
	s_lshl_b32 s4, s44, 22
	s_add_u32 s14, s62, s0
	s_addc_u32 s15, s63, s1
	s_add_u32 s34, s14, s4
	s_addc_u32 s35, s15, 0
	v_lshl_add_u64 v[96:97], s[34:35], 0, v[176:177]
	s_movk_i32 s4, 0x1000
	v_add_co_u32_e32 v96, vcc, s4, v96
	global_load_dwordx4 v[112:115], v176, s[34:35] nt
	global_load_dwordx4 v[116:119], v176, s[34:35] offset:1024 nt
	global_load_dwordx4 v[120:123], v176, s[34:35] offset:2048 nt
	global_load_dwordx4 v[124:127], v176, s[34:35] offset:3072 nt
	v_addc_co_u32_e32 v97, vcc, 0, v97, vcc
	global_load_dwordx4 v[128:131], v[96:97], off nt
	global_load_dwordx4 v[132:135], v[96:97], off offset:1024 nt
	global_load_dwordx4 v[136:139], v[96:97], off offset:2048 nt
	global_load_dwordx4 v[140:143], v[96:97], off offset:3072 nt
	s_waitcnt vmcnt(0)
	v_pk_add_f32 v[94:95], v[94:95], v[114:115]
	v_pk_add_f32 v[92:93], v[92:93], v[112:113]
	v_pk_add_f32 v[90:91], v[90:91], v[118:119]
	v_pk_add_f32 v[88:89], v[88:89], v[116:117]
	v_pk_add_f32 v[86:87], v[86:87], v[122:123]
	v_pk_add_f32 v[84:85], v[84:85], v[120:121]
	v_pk_add_f32 v[72:73], v[72:73], v[126:127]
	v_pk_add_f32 v[70:71], v[70:71], v[124:125]
	v_pk_add_f32 v[82:83], v[82:83], v[130:131]
	v_pk_add_f32 v[80:81], v[80:81], v[128:129]
	v_pk_add_f32 v[78:79], v[78:79], v[134:135]
	v_pk_add_f32 v[76:77], v[76:77], v[132:133]
	v_pk_add_f32 v[68:69], v[68:69], v[138:139]
	v_pk_add_f32 v[74:75], v[74:75], v[136:137]
	v_pk_add_f32 v[66:67], v[66:67], v[142:143]
	v_pk_add_f32 v[64:65], v[64:65], v[140:141]
